# candidate C + P4 re-deal: every workgroup takes 4 retention-output units (GEMM workgroups through the generic loop)
# baseline (speedup 1.0000x reference)
;     __host__ __device__ void init(int M, int N, int K, int G_, int c_, int tailM_, int nsplit_) { so.init(M, N, K, G_, c_); tailM = tailM_; nsplit = nsplit_; npieces = tailM_ * so.nN * nsplit_; }
; DI void retout_load(const Params& P, int ru, int tid, int wave, int lane, OutRegs& R) {
;     const bf16_t* Z = (const bf16_t*)(P.ws + WS_Z);
;     bool samp; int b, c, h, row0; ret_decode(ru, samp, b, c, h, row0);
; #pragma unroll
;     for (int i = 0; i < 2; ++i) { const int v = tid + 512 * i, j = v >> 4, d0 = (v & 15) * 8; const bf16_t* zr = Z + (size_t)(row0 + j) * INW;
;         R.q[i] = __builtin_nontemporal_load((const u32x4*)(zr + 768 + 128 * h + d0)); R.k[i] = __builtin_nontemporal_load((const u32x4*)(zr + 1280 + 128 * h + d0)); R.v[i] = __builtin_nontemporal_load((const u32x4*)(zr + 1792 + 128 * h + d0)); }
;     const bf16_t* S = (const bf16_t*)(P.ws + WS_SB) + ((size_t)(b * 32 + (c > 0 ? c - 1 : 0)) * 4 + h) * 16384;
; #pragma unroll
;     for (int i = 0; i < 4; ++i) { const int v = tid + 512 * i, dk = v >> 4, e0 = (v & 15) * 8; R.s[i] = (u32x4){0u, 0u, 0u, 0u}; if (c > 0) R.s[i] = __builtin_nontemporal_load((const u32x4*)(S + dk * 128 + e0)); }
; __global__ void __launch_bounds__(512, 2) fwd_megakernel(Params P) {
;     ...
;     if (bx < NS4) {
;         pg8::Gemm g{(const bf16_t*)(ws + WS_H1B), (const bf16_t*)(ws + WS_WUP), MT, FF, DM}; pg8::SubsetOrder S; S.init(MP / 256, FF / 256, DM, NS4, bx);
;         pg8::EpiUp E{(const float*)(ws + WS_ROWSS2), (bf16_t*)(ws + WS_U)};
;         pg8::gemm_phase<pg8::EpiUp, pg8::SubsetOrder, true, true>(lds, g, S, E, wave0);
;         { FRESH_IDS; retout_prompt_loop(lds, P, NS4, bx, tid, wave, lane, 1024 - NS4, 1024); }
;     } else { FRESH_IDS; retout_prompt_loop(lds, P, G - NS4, bx - NS4, tid, wave, lane, 0, 1024 - NS4); }
.LBB0_727:
	s_or_b64 exec, exec, s[0:1]
	s_add_u32 s46, s68, 0xda00000
	s_addc_u32 s3, s69, 0
	s_and_b64 s[0:1], s[78:79], exec
	s_cselect_b32 s49, 64, 0
	s_cmp_ge_i32 s2, s49
	s_mov_b64 s[0:1], -1
	s_waitcnt lgkmcnt(0)
	s_barrier
	s_cbranch_scc0 .LBB0_754
	s_mov_b32 s98, s2
	s_mov_b32 s99, s49
	s_mov_b32 s101, s96
	s_cmp_lg_u32 s100, 0
	s_cbranch_scc1 .Lrd_entry
	s_add_i32 s98, s2, 0xc0
	s_movk_i32 s99, 0x100
	s_movk_i32 s101, 0x1c0
.Lrd_entry:
	v_mov_b32_e32 v40, v175
	s_cmpk_gt_i32 s98, 0x3ff
	s_cbranch_scc1 .LBB0_753
	s_sub_i32 s0, s98, s99
	s_ashr_i32 s8, s0, 7
	s_bfe_u32 s9, s0, 0x50002
	s_lshl_b32 s0, s8, 11
	s_lshl_b32 s1, s9, 6
	s_or_b32 s6, s1, s0
	v_ashrrev_i32_e32 v98, 4, v40
	v_add_u32_e32 v10, 0x200, v40
	s_and_b32 s7, s98, 3
	v_lshlrev_b32_e32 v34, 3, v40
	v_add_u32_e32 v0, s6, v98
	s_movk_i32 s10, 0x1600
	v_mov_b64_e32 v[8:9], s[74:75]
	v_ashrrev_i32_e32 v99, 4, v10
	v_and_b32_e32 v2, 0x78, v34
	s_mov_b32 s1, 0
	v_mad_i64_i32 v[0:1], s[4:5], v0, s10, v[8:9]
	s_lshl_b32 s0, s7, 8
	v_add_u32_e32 v10, s6, v99
	v_mov_b32_e32 v69, 0
	v_lshl_add_u64 v[0:1], v[0:1], 0, s[0:1]
	v_lshlrev_b32_e32 v68, 1, v2
	v_mad_i64_i32 v[8:9], s[4:5], v10, s10, v[8:9]
	v_lshl_add_u64 v[24:25], v[0:1], 0, v[68:69]
	v_lshl_add_u64 v[8:9], v[8:9], 0, s[0:1]
	global_load_dwordx4 v[0:3], v[24:25], off offset:1536 nt
	global_load_dwordx4 v[4:7], v[24:25], off offset:2560 nt
	v_lshl_add_u64 v[26:27], v[8:9], 0, v[68:69]
	global_load_dwordx4 v[8:11], v[24:25], off offset:3584 nt
	global_load_dwordx4 v[12:15], v[26:27], off offset:1536 nt
	global_load_dwordx4 v[16:19], v[26:27], off offset:2560 nt
	global_load_dwordx4 v[20:23], v[26:27], off offset:3584 nt
	s_lshl_b32 s0, s8, 5
	s_max_u32 s1, s9, 1
	s_or_b32 s0, s0, s1
	s_add_i32 s0, s0, -1
	s_ashr_i32 s1, s0, 31
	s_lshl_b64 s[0:1], s[0:1], 17
	s_add_u32 s0, s46, s0
	s_addc_u32 s1, s3, s1
	s_lshl_b32 s4, s7, 15
	s_add_u32 s4, s0, s4
	s_addc_u32 s5, s1, 0
	s_cmp_lg_u32 s9, 0
	s_cselect_b64 s[0:1], -1, 0
	v_lshl_add_u64 v[32:33], s[4:5], 0, v[68:69]
	s_and_b64 vcc, exec, s[0:1]
	s_cbranch_vccz .LBB0_831
	v_and_b32_e32 v70, 0xffffff80, v34
	v_add_u32_e32 v24, 0x1000, v70
	v_ashrrev_i32_e32 v71, 31, v70
	v_ashrrev_i32_e32 v25, 31, v24
	v_lshl_add_u64 v[38:39], v[70:71], 1, v[32:33]
	v_lshl_add_u64 v[36:37], v[24:25], 1, v[32:33]
	global_load_dwordx4 v[28:31], v[38:39], off nt
	global_load_dwordx4 v[24:27], v[36:37], off nt
	s_cbranch_execnz .LBB0_732

; #define LAS __attribute__((address_space(3)))
; DI f32x4 mfma16(bf16x8 a, bf16x8 b, f32x4 c) { return __builtin_amdgcn_mfma_f32_16x16x32_bf16(a, b, c, 0, 0, 0); }
; DI bf16x8 pack8(const f32x4& a, const f32x4& b) { u32x4 w = {pk(a[0], a[1]), pk(a[2], a[3]), pk(b[0], b[1]), pk(b[2], b[3])}; return __builtin_bit_cast(bf16x8, w); }
; DI float log2_gamma(int h) { return log2f(1.0f - exp2f(-5.0f - (float)h)); }
; DI void retout_compute(lds_t* lds, const Params& P, int row0, int h, float l2g, bool has_state, int wave, int lane, const u32x2 (&gt)[4], bool wt) {
;     bf16_t* MIX = (bf16_t*)(P.ws + WS_MIX);
;     lds_t* Qs = lds; lds_t* Ks = lds + (64 * RSR); lds_t* Vs = lds + 2 * (64 * RSR); lds_t* Ss = lds + 3 * (64 * RSR); LAS float* ssx = (LAS float*)(lds + 3 * (64 * RSR) + 128 * RSR);
;     const int g = lane >> 4, l15 = lane & 15, it = wave & 3, eh = wave >> 2;
;     const int i_ = 16 * it + l15;
;     bf16x8 qf[4];
; #pragma unroll
;     for (int ks = 0; ks < 4; ++ks) qf[ks] = frag_N(Qs, RSR, 16 * it, 32 * ks, lane);
;     f32x4 p[4];
; #pragma unroll
;     for (int jt = 0; jt < 4; ++jt) {
;         f32x4 a = {0.f, 0.f, 0.f, 0.f};
;         if (jt <= it) {
; #pragma unroll
;             for (int ks = 0; ks < 4; ++ks) a = mfma16(frag_N(Ks, RSR, 16 * jt, 32 * ks, lane), qf[ks], a);
; #pragma unroll
;             for (int i = 0; i < 4; ++i) { const int j_ = 16 * jt + 4 * g + i; a[i] = (i_ >= j_) ? a[i] * exp2f((float)(i_ - j_) * l2g) : 0.f; }
;         }
;         p[jt] = a;
;     }
;     const bf16x8 pf0 = pack8(p[0], p[1]), pf1 = pack8(p[2], p[3]);
;     f32x4 acc[4];
;     const float qdec = exp2f((float)(i_ + 1) * l2g);
;     float ss = 0.f;
; #pragma unroll
;     OutRegs R; int u = u_lo + bx;
;     if (u < u_hi) retout_load(P, u, tid, wave, lane, R);
;     for (; u < u_hi; u += G) {
;         bool samp; int b, c, h, row0; ret_decode(u, samp, b, c, h, row0);
;         retout_stage(lds, tid, R);
;         u32x2 gt[4];
; #pragma unroll
;         for (int et = 0; et < 4; ++et) gt[et] = R.gt[et];
;         __syncthreads();
;         if (u + G < u_hi) retout_load(P, u + G, tid, wave, lane, R);
;         retout_compute(lds, P, row0, h, log2_gamma(h), true, wave, lane, gt, false);
.LBB0_735:
	v_readlane_b32 s0, v255, 13
	s_lshl_b32 s5, s0, 4
	v_and_b32_e32 v45, 15, v40
	v_and_or_b32 v100, s5, 48, v45
	v_or_b32_e32 v44, s6, v100
	s_movk_i32 s71, 0x1600
	v_mov_b64_e32 v[42:43], s[74:75]
	v_mad_i64_i32 v[42:43], s[0:1], v44, s71, v[42:43]
	s_lshl_b32 s40, s4, 1
	s_mov_b32 s41, 0
	s_and_b32 s38, s5, 0x3fffffc0
	v_bfe_u32 v48, v40, 2, 4
	v_lshl_add_u64 v[42:43], v[42:43], 0, s[40:41]
	s_lshl_b32 s40, s38, 1
	v_and_b32_e32 v44, 12, v48
	v_lshl_add_u64 v[42:43], v[42:43], 0, s[40:41]
	v_mov_b32_e32 v77, 0
	v_lshlrev_b32_e32 v76, 1, v44
	v_lshl_add_u64 v[42:43], v[42:43], 0, v[76:77]
	s_mov_b64 s[42:43], 0x1200
	s_movk_i32 s0, 0x1000
	v_lshl_add_u64 v[46:47], v[42:43], 0, s[42:43]
	v_add_co_u32_e32 v42, vcc, s0, v42
	s_sub_i32 s47, s101, s99
	s_nop 0
	v_addc_co_u32_e32 v43, vcc, 0, v43, vcc
	global_load_dwordx2 v[80:81], v[46:47], off offset:96
	global_load_dwordx2 v[96:97], v[42:43], off offset:512
	global_load_dwordx2 v[84:85], v[46:47], off offset:64
	global_load_dwordx2 v[86:87], v[46:47], off offset:32
	s_sub_i32 s70, 0x400, s99
	v_lshl_or_b32 v101, s48, 4, v45
	s_cmp_lg_u32 s48, 0
	v_sub_co_u32_e64 v54, s[0:1], v101, v44
	s_cselect_b64 s[44:45], -1, 0
	s_cmp_gt_u32 s48, 1
	v_and_b32_e32 v41, 63, v40
	v_lshlrev_b32_e32 v42, 4, v40
	v_add_u32_e32 v47, 0x400, v40
	v_add_u32_e32 v49, 0x600, v40
	v_and_b32_e32 v51, 48, v40
	v_cvt_f32_u32_e32 v102, v54
	v_xad_u32 v54, v44, -1, v101
	s_cselect_b64 s[50:51], -1, 0
	s_cmp_eq_u32 s48, 3
	v_lshlrev_b32_e32 v40, 2, v40
	v_cvt_f32_u32_e32 v103, v54
	v_or_b32_e32 v54, 3, v48
	v_or_b32_e32 v55, 2, v44
	s_cselect_b64 s[54:55], -1, 0
	v_and_b32_e32 v40, 12, v40
	s_or_b32 s9, s72, 16
	v_sub_u32_e32 v56, v101, v55
	v_cmp_lt_u32_e64 s[4:5], v101, v54
	v_cmp_lt_u32_e64 s[6:7], v101, v55
	v_sub_u32_e32 v54, v101, v54
	v_or_b32_e32 v55, 16, v44
	v_or_b32_e32 v76, s9, v45
	v_or_b32_e32 v82, s9, v40
	s_or_b32 s9, s72, 32
	s_movk_i32 s8, 0x110
	v_cvt_f32_ubyte0_e32 v104, v56
	v_cvt_f32_ubyte0_e32 v105, v54
	v_or_b32_e32 v54, 17, v44
	v_sub_u32_e32 v56, v101, v55
	v_lshlrev_b32_e32 v83, 1, v82
	v_or_b32_e32 v82, s9, v45
	v_cvt_f32_ubyte0_e32 v106, v56
	v_sub_u32_e32 v56, v101, v54
	v_or_b32_e32 v57, 18, v44
	v_mul_lo_u32 v88, v82, s8
	v_or_b32_e32 v82, s9, v40
	s_or_b32 s9, s72, 48
	v_cvt_f32_ubyte0_e32 v107, v56
	v_or_b32_e32 v56, 19, v48
	v_sub_u32_e32 v58, v101, v57
	v_or_b32_e32 v64, 48, v44
	v_or_b32_e32 v69, s72, v40
	v_or_b32_e32 v40, s9, v40
	v_cvt_f32_ubyte0_e32 v108, v58
	v_sub_u32_e32 v58, v101, v56
	v_or_b32_e32 v59, 32, v44
	v_or_b32_e32 v63, 49, v44
	v_sub_u32_e32 v65, v101, v64
	v_lshlrev_b32_e32 v90, 1, v40
	v_and_b32_e32 v40, 64, v201
	v_cvt_f32_ubyte0_e32 v109, v58
	v_or_b32_e32 v58, 33, v44
	v_sub_u32_e32 v60, v101, v59
	v_cvt_f32_ubyte0_e32 v114, v65
	v_sub_u32_e32 v65, v101, v63
	v_or_b32_e32 v66, 50, v44
	v_add_u32_e32 v40, 64, v40
	v_cvt_f32_ubyte0_e32 v110, v60
	v_sub_u32_e32 v60, v101, v58
	v_or_b32_e32 v61, 34, v44
	v_cvt_f32_ubyte0_e32 v115, v65
	v_or_b32_e32 v65, 51, v48
	v_sub_u32_e32 v67, v101, v66
	v_cmp_lt_i32_e32 vcc, v209, v40
	v_cvt_f32_ubyte0_e32 v111, v60
	v_or_b32_e32 v60, 35, v48
	v_sub_u32_e32 v62, v101, v61
	v_cvt_f32_ubyte0_e32 v116, v67
	v_sub_u32_e32 v67, v101, v65
	v_lshlrev_b32_e32 v89, 1, v82
	v_cndmask_b32_e32 v82, v201, v209, vcc
	v_cmp_lt_i32_e32 vcc, v254, v40
	v_readlane_b32 s10, v255, 10
	v_cvt_f32_ubyte0_e32 v112, v62
	v_sub_u32_e32 v62, v101, v60
	v_cvt_f32_ubyte0_e32 v117, v67
	v_add_u32_e32 v67, 1, v101
	v_cndmask_b32_e32 v40, v201, v254, vcc
	s_and_b32 s10, s10, 0xffffff00
	s_add_i32 s11, 0, 0x15400
	s_lshl_b32 s39, s99, 1
	v_and_b32_e32 v42, 0xf0, v42
	v_lshrrev_b32_e32 v47, 4, v47
	v_lshrrev_b32_e32 v49, 4, v49
	v_mul_u32_u24_e32 v53, 0x110, v45
	v_cvt_f32_ubyte0_e32 v113, v62
	v_or_b32_e32 v62, 48, v41
	v_cvt_f32_ubyte0_e32 v118, v67
	v_or_b32_e32 v67, s72, v45
	v_or_b32_e32 v45, s9, v45
	v_lshlrev_b32_e32 v120, 2, v40
	s_add_i32 s10, s11, s10
	v_lshlrev_b32_e32 v40, 2, v101
	s_sub_i32 s73, s101, s39
	s_lshl_b32 s39, s98, 4
	s_lshl_b32 s40, s99, 4
	v_add_u32_e32 v42, 0, v42
	v_mul_lo_u32 v43, v98, s8
	v_mul_lo_u32 v46, v99, s8
	v_mul_lo_u32 v47, v47, s8
	v_mul_lo_u32 v49, v49, s8
	v_add_u32_e32 v78, 0x1000, v70
	v_mad_u32_u24 v50, v101, s8, 0
	v_add_u32_e32 v52, 0, v51
	v_mul_u32_u24_e32 v62, 0x110, v62
	v_mad_u32_u24 v48, v48, s8, 0
	v_mul_lo_u32 v67, v67, s8
	v_lshlrev_b32_e32 v69, 1, v69
	v_mul_lo_u32 v76, v76, s8
	v_mul_lo_u32 v45, v45, s8
	v_add_u32_e32 v121, s10, v40
	v_add_u32_e32 v122, s11, v40
	v_or_b32_e32 v40, s72, v44
	s_sub_i32 s77, s39, s40
	s_lshl_b32 s39, s101, 4
	v_ashrrev_i32_e32 v71, 31, v70
	v_ashrrev_i32_e32 v79, 31, v78
	v_cmp_gt_u32_e64 s[36:37], v101, v44
	v_lshlrev_b32_e32 v119, 2, v82
	v_cmp_gt_u32_e64 s[8:9], 16, v41
	v_cmp_lt_u32_e64 s[10:11], v101, v56
	v_cmp_lt_u32_e64 s[12:13], v101, v57
	v_cmp_lt_u32_e64 s[14:15], v101, v54
	v_cmp_lt_u32_e64 s[16:17], v101, v55
	v_cmp_lt_u32_e64 s[18:19], v101, v60
	v_cmp_lt_u32_e64 s[20:21], v101, v61
	v_cmp_lt_u32_e64 s[22:23], v101, v58
	v_cmp_lt_u32_e64 s[24:25], v101, v59
	v_cmp_lt_u32_e64 s[26:27], v101, v65
	v_cmp_lt_u32_e64 s[28:29], v101, v66
	v_cmp_lt_u32_e64 s[30:31], v101, v63
	v_cmp_lt_u32_e64 s[34:35], v101, v64
	s_sub_i32 s76, 0, s99
	s_sub_i32 s80, s39, s40
	v_add_u32_e32 v123, v42, v43
	v_add_u32_e32 v124, v42, v46
	v_add_u32_e32 v125, v42, v47
	v_add_u32_e32 v126, v42, v49
	s_lshl_b32 s56, s38, 1
	v_lshlrev_b32_e32 v82, 1, v44
	s_mov_b32 s81, 0xc2fc0000
	s_mov_b32 s82, 0x800000
	v_add_u32_e32 v127, v50, v51
	v_add_u32_e32 v128, v52, v62
	s_mov_b32 s83, 0x5040100
	v_add_u32_e32 v129, v52, v67
	v_add_u32_e32 v130, v48, v69
	v_add_u32_e32 v131, v52, v76
	v_add_u32_e32 v132, v48, v83
	v_add_u32_e32 v133, v52, v88
	v_add_u32_e32 v134, v48, v89
	v_add_u32_e32 v135, v52, v45
	v_add_u32_e32 v136, v48, v90
	v_mov_b32_e32 v137, 0x358637bd
	v_lshlrev_b32_e32 v76, 1, v40
	s_mov_b64 s[58:59], 0xba00400
	s_mov_b32 s84, 0xba00000
	v_mov_b32_e32 v138, 0x42800000
	v_mov_b32_e32 v139, 0x42000000
	v_add_u32_e32 v140, v52, v53
	v_not_b32_e32 v141, 63
	s_mov_b32 s85, s98
	s_waitcnt vmcnt(3)
	v_mov_b64_e32 v[88:89], v[80:81]
	s_waitcnt vmcnt(1)
	v_mov_b64_e32 v[90:91], v[84:85]
	s_waitcnt vmcnt(0)
	v_mov_b64_e32 v[92:93], v[86:87]
	v_mov_b64_e32 v[94:95], v[96:97]
	s_branch .LBB0_737

;     __device__ __forceinline__ void operator()(const f32x4 (&acc)[2][2][4][2], const Unit& u, int wr, int wc, int fr, int fq) const {
;         float rsv[8];
; #pragma unroll
;         for (int idx = 0; idx < 8; ++idx) { const f32x4 q = *(const f32x4*)(rowss + (size_t)(u.pm * BM + (idx >> 2) * HALF + wr * 64 + (idx & 3) * 16 + fr) * 4); rsv[idx] = (q[0] + q[1]) + (q[2] + q[3]); }
; #pragma unroll
;         for (int ai = 0; ai < 2; ++ai)
; #pragma unroll
;             for (int m = 0; m < 4; ++m) {
;                 const int r = u.pm * BM + ai * HALF + wr * 64 + m * 16 + fr;
;                 const float rs = rsqrtf(rsv[ai * 4 + m] * (1.0f / DM) + EPS);
; #pragma unroll
;                 for (int bj = 0; bj < 2; ++bj) {
;                     f32x4 a = acc[ai][bj][m][0] * rs, b = acc[ai][bj][m][1] * rs;
; #pragma unroll
;                     for (int t = 0; t < 4; ++t) { a[t] = fmaxf(a[t], 0.f); a[t] *= a[t]; b[t] = fmaxf(b[t], 0.f); b[t] *= b[t]; }
;                     st8bf(U + (size_t)r * FF + u.pn * BM + wc * 64 + bj * 32 + 8 * fq, a, b);
;                 }
;             }
;     }
.Lsp4_nowait:
	s_barrier
	s_add_u32 s6, s68, 0x120000
	v_lshl_add_u32 v130, s4, 8, v129
	s_addc_u32 s7, s69, 0
	v_ashrrev_i32_e32 v131, 31, v130
	v_or_b32_e32 v148, 16, v130
	v_lshl_add_u64 v[132:133], v[130:131], 4, s[6:7]
	v_ashrrev_i32_e32 v149, 31, v148
	v_or_b32_e32 v146, 32, v130
	v_lshl_add_u64 v[138:139], v[148:149], 4, s[6:7]
	global_load_dwordx4 v[134:137], v[132:133], off
	global_load_dwordx4 v[142:145], v[138:139], off
	v_ashrrev_i32_e32 v147, 31, v146
	v_or_b32_e32 v140, 48, v130
	v_lshl_add_u64 v[132:133], v[146:147], 4, s[6:7]
	v_ashrrev_i32_e32 v141, 31, v140
	v_lshl_add_u64 v[138:139], v[140:141], 4, s[6:7]
	global_load_dwordx4 v[150:153], v[132:133], off
	global_load_dwordx4 v[154:157], v[138:139], off
	v_add_u32_e32 v138, 0x80, v130
	v_add_u32_e32 v158, 0x90, v130
	v_ashrrev_i32_e32 v139, 31, v138
	v_ashrrev_i32_e32 v159, 31, v158
	v_lshl_add_u64 v[132:133], v[138:139], 4, s[6:7]
	v_lshl_add_u64 v[162:163], v[158:159], 4, s[6:7]
	global_load_dwordx4 v[158:161], v[132:133], off
	s_nop 0
	global_load_dwordx4 v[162:165], v[162:163], off
	v_add_u32_e32 v132, 0xa0, v130
	v_ashrrev_i32_e32 v133, 31, v132
	v_lshl_add_u64 v[132:133], v[132:133], 4, s[6:7]
	global_load_dwordx4 v[166:169], v[132:133], off
	v_add_u32_e32 v132, 0xb0, v130
	v_ashrrev_i32_e32 v133, 31, v132
	v_lshl_add_u64 v[132:133], v[132:133], 4, s[6:7]
	s_mov_b32 s8, 0x358637bd
	global_load_dwordx4 v[170:173], v[132:133], off
	s_mov_b32 s4, 0x3a800000
	s_mov_b32 s5, 0x800000
	v_mov_b64_e32 v[132:133], s[8:9]
	s_add_u32 s10, s68, 0x3200000
	s_addc_u32 s11, s69, 0
	s_lshl_b32 s8, s0, 8
	v_lshlrev_b64 v[130:131], 13, v[130:131]
	s_ashr_i32 s9, s8, 31
	v_lshl_add_u64 v[130:131], s[10:11], 0, v[130:131]
	s_lshl_b64 s[8:9], s[8:9], 1
	s_mov_b32 s1, 0
	s_lshl_b32 s0, s48, 7
	v_lshl_add_u64 v[130:131], v[130:131], 0, s[8:9]
	v_mov_b32_e32 v129, 0
	v_lshl_add_u64 v[130:131], v[130:131], 0, s[0:1]
	v_lshl_add_u64 v[130:131], v[130:131], 0, v[128:129]
	s_mov_b64 s[6:7], 0x120000
	s_waitcnt vmcnt(0)
	v_mov_b32_e32 v176, v135
	v_mov_b32_e32 v177, v136
	v_mov_b32_e32 v135, v137
	v_mov_b32_e32 v136, v143
	v_mov_b32_e32 v137, v144
	v_mov_b32_e32 v143, v145
	v_pk_add_f32 v[134:135], v[176:177], v[134:135]
	v_mov_b32_e32 v144, v151
	v_mov_b32_e32 v145, v152
	v_mov_b32_e32 v151, v153
	v_pk_add_f32 v[136:137], v[136:137], v[142:143]
	v_pk_add_f32 v[150:151], v[144:145], v[150:151]
	v_mov_b32_e32 v145, v134
	v_mov_b32_e32 v144, v136
	v_mov_b32_e32 v134, v137
	v_mov_b32_e32 v152, v155
	v_mov_b32_e32 v153, v156
	v_mov_b32_e32 v155, v157
	v_pk_add_f32 v[134:135], v[144:145], v[134:135]
	v_pk_add_f32 v[152:153], v[152:153], v[154:155]
	v_pk_fma_f32 v[154:155], v[134:135], s[4:5], v[132:133] op_sel_hi:[1,0,0]
	v_mov_b32_e32 v156, v159
	v_mul_f32_e32 v134, 0x4b800000, v155
	v_cmp_gt_f32_e32 vcc, s5, v155
	v_mov_b32_e32 v157, v160
	v_mov_b32_e32 v159, v161
	v_cndmask_b32_e32 v134, v155, v134, vcc
	v_rsq_f32_e32 v155, v134
	v_pk_add_f32 v[142:143], v[156:157], v[158:159]
	v_mov_b32_e32 v160, v163
	v_mov_b32_e32 v161, v164
	v_mul_f32_e32 v156, 0x45800000, v155
	v_cndmask_b32_e32 v156, v155, v156, vcc
	v_pk_mul_f32 v[120:121], v[120:121], v[156:157] op_sel_hi:[1,0]
	v_pk_mul_f32 v[126:127], v[126:127], v[156:157] op_sel_hi:[1,0]
	v_pk_mul_f32 v[124:125], v[124:125], v[156:157] op_sel_hi:[1,0]
	v_pk_mul_f32 v[122:123], v[122:123], v[156:157] op_sel_hi:[1,0]
	v_max_f32_e32 v120, 0, v120
	v_max_f32_e32 v121, 0, v121
	v_mov_b32_e32 v163, v165
	v_max_f32_e32 v124, 0, v124
	v_max_f32_e32 v125, 0, v125
	v_pk_mul_f32 v[158:159], v[120:121], v[120:121]
	v_max_f32_e32 v120, 0, v126
	v_max_f32_e32 v122, 0, v122
	v_max_f32_e32 v121, 0, v127
	v_max_f32_e32 v123, 0, v123
	v_pk_add_f32 v[144:145], v[160:161], v[162:163]
	v_pk_mul_f32 v[124:125], v[124:125], v[124:125]
	v_pk_mul_f32 v[126:127], v[120:121], v[120:121]
	v_pk_mul_f32 v[160:161], v[122:123], v[122:123]
	v_pk_mul_f32 v[114:115], v[114:115], v[156:157] op_sel_hi:[1,0]
	v_cvt_pk_bf16_f32 v120, v124, v125
	v_cvt_pk_bf16_f32 v121, v126, v127
	v_cvt_pk_bf16_f32 v122, v158, v159
	v_cvt_pk_bf16_f32 v123, v160, v161
	v_pk_mul_f32 v[116:117], v[116:117], v[156:157] op_sel_hi:[1,0]
	v_pk_mul_f32 v[112:113], v[112:113], v[156:157] op_sel_hi:[1,0]
	v_max_f32_e32 v114, 0, v114
	v_max_f32_e32 v115, 0, v115
	global_store_dwordx4 v[130:131], v[120:123], off
	v_pk_mul_f32 v[118:119], v[118:119], v[156:157] op_sel_hi:[1,0]
	v_max_f32_e32 v116, 0, v116
	v_max_f32_e32 v112, 0, v112
	v_max_f32_e32 v117, 0, v117
	v_max_f32_e32 v113, 0, v113
	v_pk_mul_f32 v[122:123], v[114:115], v[114:115]
	v_mul_f32_e32 v114, 0x4b800000, v154
	v_cmp_gt_f32_e32 vcc, s5, v154
	v_pk_mul_f32 v[116:117], v[116:117], v[116:117]
	v_pk_mul_f32 v[120:121], v[112:113], v[112:113]
	v_max_f32_e32 v112, 0, v118
	v_max_f32_e32 v113, 0, v119
	v_cndmask_b32_e32 v114, v154, v114, vcc
	v_pk_mul_f32 v[118:119], v[112:113], v[112:113]
	v_cvt_pk_bf16_f32 v112, v116, v117
	v_rsq_f32_e32 v116, v114
	v_cvt_pk_bf16_f32 v113, v118, v119
	v_cvt_pk_bf16_f32 v114, v120, v121
	v_cvt_pk_bf16_f32 v115, v122, v123
	global_store_dwordx4 v[130:131], v[112:115], off offset:64
	v_mov_b32_e32 v164, v167
	v_mov_b32_e32 v165, v168
	v_mul_f32_e32 v112, 0x45800000, v116
	v_cndmask_b32_e32 v112, v116, v112, vcc
	v_pk_mul_f32 v[104:105], v[104:105], v[112:113] op_sel_hi:[1,0]
	v_pk_mul_f32 v[110:111], v[110:111], v[112:113] op_sel_hi:[1,0]
	v_max_f32_e32 v104, 0, v104
	v_max_f32_e32 v105, 0, v105
	v_lshlrev_b64 v[114:115], 13, v[148:149]
	v_pk_mul_f32 v[116:117], v[104:105], v[104:105]
	v_max_f32_e32 v104, 0, v110
	v_max_f32_e32 v105, 0, v111
	v_pk_mul_f32 v[108:109], v[108:109], v[112:113] op_sel_hi:[1,0]
;     __device__ __forceinline__ void operator()(const f32x4 (&acc)[2][2][4][2], const Unit& u, int wr, int wc, int fr, int fq) const {
;         float rsv[8];
; #pragma unroll
;         for (int idx = 0; idx < 8; ++idx) { const f32x4 q = *(const f32x4*)(rowss + (size_t)(u.pm * BM + (idx >> 2) * HALF + wr * 64 + (idx & 3) * 16 + fr) * 4); rsv[idx] = (q[0] + q[1]) + (q[2] + q[3]); }
; #pragma unroll
;         for (int ai = 0; ai < 2; ++ai)
; #pragma unroll
;             for (int m = 0; m < 4; ++m) {
;                 const int r = u.pm * BM + ai * HALF + wr * 64 + m * 16 + fr;
;                 const float rs = rsqrtf(rsv[ai * 4 + m] * (1.0f / DM) + EPS);
; #pragma unroll
;                 for (int bj = 0; bj < 2; ++bj) {
;                     f32x4 a = acc[ai][bj][m][0] * rs, b = acc[ai][bj][m][1] * rs;
; #pragma unroll
;                     for (int t = 0; t < 4; ++t) { a[t] = fmaxf(a[t], 0.f); a[t] *= a[t]; b[t] = fmaxf(b[t], 0.f); b[t] *= b[t]; }
;                     st8bf(U + (size_t)r * FF + u.pn * BM + wc * 64 + bj * 32 + 8 * fq, a, b);
;                 }
;             }
;     }
	v_pk_mul_f32 v[106:107], v[106:107], v[112:113] op_sel_hi:[1,0]
	v_pk_mul_f32 v[110:111], v[104:105], v[104:105]
	v_lshl_add_u64 v[104:105], s[10:11], 0, v[114:115]
	v_max_f32_e32 v108, 0, v108
	v_max_f32_e32 v109, 0, v109
	v_max_f32_e32 v106, 0, v106
	v_max_f32_e32 v107, 0, v107
	v_lshl_add_u64 v[104:105], v[104:105], 0, s[8:9]
	v_pk_mul_f32 v[108:109], v[108:109], v[108:109]
	v_pk_mul_f32 v[118:119], v[106:107], v[106:107]
	v_lshl_add_u64 v[104:105], v[104:105], 0, s[0:1]
	v_pk_mul_f32 v[96:97], v[96:97], v[112:113] op_sel_hi:[1,0]
	v_lshl_add_u64 v[114:115], v[104:105], 0, v[128:129]
	v_cvt_pk_bf16_f32 v104, v108, v109
	v_cvt_pk_bf16_f32 v105, v110, v111
	v_cvt_pk_bf16_f32 v106, v116, v117
	v_cvt_pk_bf16_f32 v107, v118, v119
	v_pk_mul_f32 v[102:103], v[102:103], v[112:113] op_sel_hi:[1,0]
	v_pk_mul_f32 v[100:101], v[100:101], v[112:113] op_sel_hi:[1,0]
	v_pk_mul_f32 v[98:99], v[98:99], v[112:113] op_sel_hi:[1,0]
	v_max_f32_e32 v96, 0, v96
	v_max_f32_e32 v97, 0, v97
	global_store_dwordx4 v[114:115], v[104:107], off
	v_max_f32_e32 v100, 0, v100
	v_max_f32_e32 v101, 0, v101
	v_pk_mul_f32 v[104:105], v[96:97], v[96:97]
	v_max_f32_e32 v96, 0, v102
	v_max_f32_e32 v98, 0, v98
	v_max_f32_e32 v97, 0, v103
	v_max_f32_e32 v99, 0, v99
	v_pk_mul_f32 v[100:101], v[100:101], v[100:101]
	v_pk_mul_f32 v[102:103], v[96:97], v[96:97]
	v_pk_mul_f32 v[106:107], v[98:99], v[98:99]
	v_cvt_pk_bf16_f32 v96, v100, v101
	v_cvt_pk_bf16_f32 v97, v102, v103
	v_cvt_pk_bf16_f32 v98, v104, v105
	v_cvt_pk_bf16_f32 v99, v106, v107
	global_store_dwordx4 v[114:115], v[96:99], off offset:64
	v_mov_b32_e32 v167, v169
	v_mov_b32_e32 v168, v171
	v_mov_b32_e32 v98, v152
	v_mov_b32_e32 v99, v150
	v_mov_b32_e32 v150, v153
	v_pk_add_f32 v[98:99], v[98:99], v[150:151]
	v_lshlrev_b64 v[96:97], 13, v[146:147]
	v_pk_fma_f32 v[98:99], v[98:99], s[4:5], v[132:133] op_sel_hi:[1,0,0]
	v_lshl_add_u64 v[96:97], s[10:11], 0, v[96:97]
	v_mul_f32_e32 v100, 0x4b800000, v99
	v_cmp_gt_f32_e32 vcc, s5, v99
	v_lshl_add_u64 v[96:97], v[96:97], 0, s[8:9]
	v_lshl_add_u64 v[96:97], v[96:97], 0, s[0:1]
	v_cndmask_b32_e32 v99, v99, v100, vcc
	v_rsq_f32_e32 v99, v99
	v_lshl_add_u64 v[96:97], v[96:97], 0, v[128:129]
	v_mov_b32_e32 v169, v172
	v_mov_b32_e32 v171, v173
	v_mul_f32_e32 v100, 0x45800000, v99
	v_cndmask_b32_e32 v100, v99, v100, vcc
	v_pk_mul_f32 v[88:89], v[88:89], v[100:101] op_sel_hi:[1,0]
	v_pk_mul_f32 v[94:95], v[94:95], v[100:101] op_sel_hi:[1,0]
	v_pk_mul_f32 v[92:93], v[92:93], v[100:101] op_sel_hi:[1,0]
	v_pk_mul_f32 v[90:91], v[90:91], v[100:101] op_sel_hi:[1,0]
	v_max_f32_e32 v88, 0, v88
	v_max_f32_e32 v89, 0, v89
	v_max_f32_e32 v92, 0, v92
	v_max_f32_e32 v93, 0, v93
	v_pk_mul_f32 v[102:103], v[88:89], v[88:89]
	v_max_f32_e32 v88, 0, v94
	v_max_f32_e32 v90, 0, v90
	v_max_f32_e32 v89, 0, v95
	v_max_f32_e32 v91, 0, v91
	v_pk_mul_f32 v[92:93], v[92:93], v[92:93]
	v_pk_mul_f32 v[94:95], v[88:89], v[88:89]
	v_pk_mul_f32 v[104:105], v[90:91], v[90:91]
	v_pk_mul_f32 v[82:83], v[82:83], v[100:101] op_sel_hi:[1,0]
	v_cvt_pk_bf16_f32 v88, v92, v93
	v_cvt_pk_bf16_f32 v89, v94, v95
	v_cvt_pk_bf16_f32 v90, v102, v103
	v_cvt_pk_bf16_f32 v91, v104, v105
	v_pk_mul_f32 v[84:85], v[84:85], v[100:101] op_sel_hi:[1,0]
	v_pk_mul_f32 v[80:81], v[80:81], v[100:101] op_sel_hi:[1,0]
	v_max_f32_e32 v82, 0, v82
	v_max_f32_e32 v83, 0, v83
	global_store_dwordx4 v[96:97], v[88:91], off
	v_pk_mul_f32 v[86:87], v[86:87], v[100:101] op_sel_hi:[1,0]
	v_max_f32_e32 v84, 0, v84
	v_max_f32_e32 v80, 0, v80
	v_max_f32_e32 v85, 0, v85
	v_max_f32_e32 v81, 0, v81
	v_pk_mul_f32 v[90:91], v[82:83], v[82:83]
	v_mul_f32_e32 v82, 0x4b800000, v98
	v_cmp_gt_f32_e32 vcc, s5, v98
	v_pk_mul_f32 v[84:85], v[84:85], v[84:85]
	v_pk_mul_f32 v[88:89], v[80:81], v[80:81]
	v_max_f32_e32 v80, 0, v86
	v_max_f32_e32 v81, 0, v87
	v_cndmask_b32_e32 v82, v98, v82, vcc
	v_pk_mul_f32 v[86:87], v[80:81], v[80:81]
	v_cvt_pk_bf16_f32 v80, v84, v85
	v_rsq_f32_e32 v84, v82
	v_cvt_pk_bf16_f32 v81, v86, v87
	v_cvt_pk_bf16_f32 v82, v88, v89
	v_cvt_pk_bf16_f32 v83, v90, v91
	global_store_dwordx4 v[96:97], v[80:83], off offset:64
	v_pk_add_f32 v[134:135], v[164:165], v[166:167]
	v_pk_add_f32 v[136:137], v[168:169], v[170:171]
	v_mul_f32_e32 v80, 0x45800000, v84
	v_cndmask_b32_e32 v80, v84, v80, vcc
	v_pk_mul_f32 v[72:73], v[72:73], v[80:81] op_sel_hi:[1,0]
	v_pk_mul_f32 v[78:79], v[78:79], v[80:81] op_sel_hi:[1,0]
	v_max_f32_e32 v72, 0, v72
	v_max_f32_e32 v73, 0, v73
	v_lshlrev_b64 v[82:83], 13, v[140:141]
	v_pk_mul_f32 v[84:85], v[72:73], v[72:73]
	v_max_f32_e32 v72, 0, v78
	v_max_f32_e32 v73, 0, v79
	v_pk_mul_f32 v[76:77], v[76:77], v[80:81] op_sel_hi:[1,0]
	v_pk_mul_f32 v[74:75], v[74:75], v[80:81] op_sel_hi:[1,0]
	v_pk_mul_f32 v[78:79], v[72:73], v[72:73]
	v_lshl_add_u64 v[72:73], s[10:11], 0, v[82:83]
	v_max_f32_e32 v76, 0, v76
	v_max_f32_e32 v77, 0, v77
	v_max_f32_e32 v74, 0, v74
	v_max_f32_e32 v75, 0, v75
	v_lshl_add_u64 v[72:73], v[72:73], 0, s[8:9]
	v_pk_mul_f32 v[76:77], v[76:77], v[76:77]
	v_pk_mul_f32 v[86:87], v[74:75], v[74:75]
	v_lshl_add_u64 v[72:73], v[72:73], 0, s[0:1]
	v_pk_mul_f32 v[64:65], v[64:65], v[80:81] op_sel_hi:[1,0]
	v_lshl_add_u64 v[82:83], v[72:73], 0, v[128:129]
	v_cvt_pk_bf16_f32 v72, v76, v77
	v_cvt_pk_bf16_f32 v73, v78, v79
	v_cvt_pk_bf16_f32 v74, v84, v85
	v_cvt_pk_bf16_f32 v75, v86, v87
	v_pk_mul_f32 v[70:71], v[70:71], v[80:81] op_sel_hi:[1,0]
	v_pk_mul_f32 v[68:69], v[68:69], v[80:81] op_sel_hi:[1,0]
	v_pk_mul_f32 v[66:67], v[66:67], v[80:81] op_sel_hi:[1,0]
	v_max_f32_e32 v64, 0, v64
	v_max_f32_e32 v65, 0, v65
	global_store_dwordx4 v[82:83], v[72:75], off
	v_max_f32_e32 v68, 0, v68
	v_max_f32_e32 v69, 0, v69
;     __device__ __forceinline__ void operator()(const f32x4 (&acc)[2][2][4][2], const Unit& u, int wr, int wc, int fr, int fq) const {
;         float rsv[8];
; #pragma unroll
;         for (int idx = 0; idx < 8; ++idx) { const f32x4 q = *(const f32x4*)(rowss + (size_t)(u.pm * BM + (idx >> 2) * HALF + wr * 64 + (idx & 3) * 16 + fr) * 4); rsv[idx] = (q[0] + q[1]) + (q[2] + q[3]); }
; #pragma unroll
;         for (int ai = 0; ai < 2; ++ai)
; #pragma unroll
;             for (int m = 0; m < 4; ++m) {
;                 const int r = u.pm * BM + ai * HALF + wr * 64 + m * 16 + fr;
;                 const float rs = rsqrtf(rsv[ai * 4 + m] * (1.0f / DM) + EPS);
; #pragma unroll
;                 for (int bj = 0; bj < 2; ++bj) {
;                     f32x4 a = acc[ai][bj][m][0] * rs, b = acc[ai][bj][m][1] * rs;
; #pragma unroll
;                     for (int t = 0; t < 4; ++t) { a[t] = fmaxf(a[t], 0.f); a[t] *= a[t]; b[t] = fmaxf(b[t], 0.f); b[t] *= b[t]; }
;                     st8bf(U + (size_t)r * FF + u.pn * BM + wc * 64 + bj * 32 + 8 * fq, a, b);
;                 }
;             }
;     }
	v_pk_mul_f32 v[72:73], v[64:65], v[64:65]
	v_max_f32_e32 v64, 0, v70
	v_max_f32_e32 v66, 0, v66
	v_max_f32_e32 v65, 0, v71
	v_max_f32_e32 v67, 0, v67
	v_pk_mul_f32 v[68:69], v[68:69], v[68:69]
	v_pk_mul_f32 v[70:71], v[64:65], v[64:65]
	v_pk_mul_f32 v[74:75], v[66:67], v[66:67]
	v_cvt_pk_bf16_f32 v64, v68, v69
	v_cvt_pk_bf16_f32 v65, v70, v71
	v_cvt_pk_bf16_f32 v66, v72, v73
	v_cvt_pk_bf16_f32 v67, v74, v75
	global_store_dwordx4 v[82:83], v[64:67], off offset:64
	s_nop 1
	v_mov_b32_e32 v66, v144
	v_mov_b32_e32 v67, v142
	v_mov_b32_e32 v142, v145
	v_pk_add_f32 v[66:67], v[66:67], v[142:143]
	v_lshlrev_b64 v[64:65], 13, v[138:139]
	v_pk_fma_f32 v[66:67], v[66:67], s[4:5], v[132:133] op_sel_hi:[1,0,0]
	v_lshl_add_u64 v[64:65], s[10:11], 0, v[64:65]
	v_mul_f32_e32 v68, 0x4b800000, v67
	v_cmp_gt_f32_e32 vcc, s5, v67
	v_lshl_add_u64 v[64:65], v[64:65], 0, s[8:9]
	v_lshl_add_u64 v[64:65], v[64:65], 0, s[0:1]
	v_cndmask_b32_e32 v67, v67, v68, vcc
	v_rsq_f32_e32 v67, v67
	v_lshl_add_u64 v[64:65], v[64:65], 0, v[128:129]
	s_mov_b32 s0, 0x120000
	v_mul_f32_e32 v68, 0x45800000, v67
	v_cndmask_b32_e32 v68, v67, v68, vcc
	v_pk_mul_f32 v[56:57], v[56:57], v[68:69] op_sel_hi:[1,0]
	v_pk_mul_f32 v[62:63], v[62:63], v[68:69] op_sel_hi:[1,0]
	v_pk_mul_f32 v[60:61], v[60:61], v[68:69] op_sel_hi:[1,0]
	v_pk_mul_f32 v[58:59], v[58:59], v[68:69] op_sel_hi:[1,0]
	v_max_f32_e32 v56, 0, v56
	v_max_f32_e32 v57, 0, v57
	v_max_f32_e32 v60, 0, v60
	v_max_f32_e32 v61, 0, v61
	v_pk_mul_f32 v[70:71], v[56:57], v[56:57]
	v_max_f32_e32 v56, 0, v62
	v_max_f32_e32 v58, 0, v58
	v_max_f32_e32 v57, 0, v63
	v_max_f32_e32 v59, 0, v59
	v_pk_mul_f32 v[60:61], v[60:61], v[60:61]
	v_pk_mul_f32 v[62:63], v[56:57], v[56:57]
	v_pk_mul_f32 v[72:73], v[58:59], v[58:59]
	v_pk_mul_f32 v[50:51], v[50:51], v[68:69] op_sel_hi:[1,0]
	v_cvt_pk_bf16_f32 v56, v60, v61
	v_cvt_pk_bf16_f32 v57, v62, v63
	v_cvt_pk_bf16_f32 v58, v70, v71
	v_cvt_pk_bf16_f32 v59, v72, v73
	v_pk_mul_f32 v[52:53], v[52:53], v[68:69] op_sel_hi:[1,0]
	v_pk_mul_f32 v[48:49], v[48:49], v[68:69] op_sel_hi:[1,0]
	v_max_f32_e32 v50, 0, v50
	v_max_f32_e32 v51, 0, v51
	global_store_dwordx4 v[64:65], v[56:59], off
	v_pk_mul_f32 v[54:55], v[54:55], v[68:69] op_sel_hi:[1,0]
	v_max_f32_e32 v52, 0, v52
	v_max_f32_e32 v48, 0, v48
	v_max_f32_e32 v53, 0, v53
	v_max_f32_e32 v49, 0, v49
	v_pk_mul_f32 v[58:59], v[50:51], v[50:51]
	v_mul_f32_e32 v50, 0x4b800000, v66
	v_cmp_gt_f32_e32 vcc, s5, v66
	v_pk_mul_f32 v[52:53], v[52:53], v[52:53]
	v_pk_mul_f32 v[56:57], v[48:49], v[48:49]
	v_max_f32_e32 v48, 0, v54
	v_max_f32_e32 v49, 0, v55
	v_cndmask_b32_e32 v50, v66, v50, vcc
	v_pk_mul_f32 v[54:55], v[48:49], v[48:49]
	v_cvt_pk_bf16_f32 v48, v52, v53
	v_rsq_f32_e32 v52, v50
	v_cvt_pk_bf16_f32 v49, v54, v55
	v_cvt_pk_bf16_f32 v50, v56, v57
	v_cvt_pk_bf16_f32 v51, v58, v59
	global_store_dwordx4 v[64:65], v[48:51], off offset:64
	v_lshl_add_u64 v[54:55], v[130:131], 0, s[6:7]
	s_mov_b64 s[6:7], 0x140000
	v_mul_f32_e32 v48, 0x45800000, v52
	v_cndmask_b32_e32 v48, v52, v48, vcc
	v_pk_mul_f32 v[44:45], v[44:45], v[48:49] op_sel_hi:[1,0]
	v_pk_mul_f32 v[40:41], v[40:41], v[48:49] op_sel_hi:[1,0]
	v_pk_mul_f32 v[46:47], v[46:47], v[48:49] op_sel_hi:[1,0]
	v_pk_mul_f32 v[42:43], v[42:43], v[48:49] op_sel_hi:[1,0]
	v_max_f32_e32 v44, 0, v44
	v_max_f32_e32 v40, 0, v40
	v_max_f32_e32 v45, 0, v45
	v_max_f32_e32 v41, 0, v41
	v_pk_mul_f32 v[44:45], v[44:45], v[44:45]
	v_pk_mul_f32 v[50:51], v[40:41], v[40:41]
	v_max_f32_e32 v40, 0, v46
	v_max_f32_e32 v42, 0, v42
	v_max_f32_e32 v41, 0, v47
	v_max_f32_e32 v43, 0, v43
	v_pk_mul_f32 v[46:47], v[40:41], v[40:41]
	v_pk_mul_f32 v[52:53], v[42:43], v[42:43]
	v_cvt_pk_bf16_f32 v40, v44, v45
	v_add_co_u32_e32 v44, vcc, s0, v130
	v_pk_mul_f32 v[32:33], v[32:33], v[48:49] op_sel_hi:[1,0]
	v_cvt_pk_bf16_f32 v41, v46, v47
	v_cvt_pk_bf16_f32 v42, v50, v51
	v_cvt_pk_bf16_f32 v43, v52, v53
	v_addc_co_u32_e32 v45, vcc, 0, v131, vcc
	v_pk_mul_f32 v[38:39], v[38:39], v[48:49] op_sel_hi:[1,0]
	v_pk_mul_f32 v[36:37], v[36:37], v[48:49] op_sel_hi:[1,0]
	v_pk_mul_f32 v[34:35], v[34:35], v[48:49] op_sel_hi:[1,0]
	v_max_f32_e32 v32, 0, v32
	v_max_f32_e32 v33, 0, v33
	global_store_dwordx4 v[44:45], v[40:43], off
	v_max_f32_e32 v36, 0, v36
	v_max_f32_e32 v37, 0, v37
	v_pk_mul_f32 v[40:41], v[32:33], v[32:33]
	v_max_f32_e32 v32, 0, v38
	v_max_f32_e32 v34, 0, v34
	v_max_f32_e32 v33, 0, v39
	v_max_f32_e32 v35, 0, v35
	v_pk_mul_f32 v[36:37], v[36:37], v[36:37]
	v_pk_mul_f32 v[38:39], v[32:33], v[32:33]
	v_pk_mul_f32 v[42:43], v[34:35], v[34:35]
	v_cvt_pk_bf16_f32 v32, v36, v37
	v_cvt_pk_bf16_f32 v33, v38, v39
	v_cvt_pk_bf16_f32 v34, v40, v41
	v_cvt_pk_bf16_f32 v35, v42, v43
	global_store_dwordx4 v[54:55], v[32:35], off offset:64
	s_mov_b32 s0, 0x140000
	s_nop 0
	v_mov_b32_e32 v32, v136
	v_mov_b32_e32 v33, v134
	v_mov_b32_e32 v134, v137
	v_pk_add_f32 v[32:33], v[32:33], v[134:135]
	s_nop 0
	v_pk_fma_f32 v[32:33], v[32:33], s[4:5], v[132:133] op_sel_hi:[1,0,0]
	s_nop 0
	v_mul_f32_e32 v34, 0x4b800000, v33
	v_cmp_gt_f32_e32 vcc, s5, v33
	s_nop 1
	v_cndmask_b32_e32 v33, v33, v34, vcc
	v_rsq_f32_e32 v33, v33
	v_lshl_add_u64 v[34:35], v[130:131], 0, s[6:7]
	v_mul_f32_e32 v36, 0x45800000, v33
	v_cndmask_b32_e32 v36, v33, v36, vcc
	v_pk_mul_f32 v[28:29], v[28:29], v[36:37] op_sel_hi:[1,0]
	v_pk_mul_f32 v[24:25], v[24:25], v[36:37] op_sel_hi:[1,0]
	v_pk_mul_f32 v[30:31], v[30:31], v[36:37] op_sel_hi:[1,0]
	v_pk_mul_f32 v[26:27], v[26:27], v[36:37] op_sel_hi:[1,0]
	v_max_f32_e32 v28, 0, v28
	v_max_f32_e32 v24, 0, v24
;     __device__ __forceinline__ void operator()(const f32x4 (&acc)[2][2][4][2], const Unit& u, int wr, int wc, int fr, int fq) const {
;     ...
;                 const float rs = rsqrtf(rsv[ai * 4 + m] * (1.0f / DM) + EPS);
; #pragma unroll
;                 for (int bj = 0; bj < 2; ++bj) {
;                     f32x4 a = acc[ai][bj][m][0] * rs, b = acc[ai][bj][m][1] * rs;
; #pragma unroll
;                     for (int t = 0; t < 4; ++t) { a[t] = fmaxf(a[t], 0.f); a[t] *= a[t]; b[t] = fmaxf(b[t], 0.f); b[t] *= b[t]; }
;                     st8bf(U + (size_t)r * FF + u.pn * BM + wc * 64 + bj * 32 + 8 * fq, a, b);
;                 }
;             }
;     }
; DI void retout_load(const Params& P, int ru, int tid, int wave, int lane, OutRegs& R) {
;     const bf16_t* Z = (const bf16_t*)(P.ws + WS_Z);
;     bool samp; int b, c, h, row0; ret_decode(ru, samp, b, c, h, row0);
; #pragma unroll
;     for (int i = 0; i < 2; ++i) { const int v = tid + 512 * i, j = v >> 4, d0 = (v & 15) * 8; const bf16_t* zr = Z + (size_t)(row0 + j) * INW;
;         R.q[i] = __builtin_nontemporal_load((const u32x4*)(zr + 768 + 128 * h + d0)); R.k[i] = __builtin_nontemporal_load((const u32x4*)(zr + 1280 + 128 * h + d0)); R.v[i] = __builtin_nontemporal_load((const u32x4*)(zr + 1792 + 128 * h + d0)); }
;     const bf16_t* S = (const bf16_t*)(P.ws + WS_SB) + ((size_t)(b * 32 + (c > 0 ? c - 1 : 0)) * 4 + h) * 16384;
; #pragma unroll
;     for (int i = 0; i < 4; ++i) { const int v = tid + 512 * i, dk = v >> 4, e0 = (v & 15) * 8; R.s[i] = (u32x4){0u, 0u, 0u, 0u}; if (c > 0) R.s[i] = __builtin_nontemporal_load((const u32x4*)(S + dk * 128 + e0)); }
	v_max_f32_e32 v29, 0, v29
	v_max_f32_e32 v25, 0, v25
	v_pk_mul_f32 v[28:29], v[28:29], v[28:29]
	v_pk_mul_f32 v[38:39], v[24:25], v[24:25]
	v_max_f32_e32 v24, 0, v30
	v_max_f32_e32 v26, 0, v26
	v_max_f32_e32 v25, 0, v31
	v_max_f32_e32 v27, 0, v27
	v_pk_mul_f32 v[30:31], v[24:25], v[24:25]
	v_pk_mul_f32 v[40:41], v[26:27], v[26:27]
	v_cvt_pk_bf16_f32 v24, v28, v29
	v_add_co_u32_e32 v28, vcc, s0, v130
	v_pk_mul_f32 v[18:19], v[18:19], v[36:37] op_sel_hi:[1,0]
	v_cvt_pk_bf16_f32 v25, v30, v31
	v_cvt_pk_bf16_f32 v26, v38, v39
	v_cvt_pk_bf16_f32 v27, v40, v41
	v_addc_co_u32_e32 v29, vcc, 0, v131, vcc
	v_pk_mul_f32 v[20:21], v[20:21], v[36:37] op_sel_hi:[1,0]
	v_pk_mul_f32 v[16:17], v[16:17], v[36:37] op_sel_hi:[1,0]
	v_max_f32_e32 v18, 0, v18
	v_max_f32_e32 v19, 0, v19
	global_store_dwordx4 v[28:29], v[24:27], off
	v_pk_mul_f32 v[22:23], v[22:23], v[36:37] op_sel_hi:[1,0]
	v_max_f32_e32 v20, 0, v20
	v_max_f32_e32 v16, 0, v16
	v_max_f32_e32 v21, 0, v21
	v_max_f32_e32 v17, 0, v17
	v_pk_mul_f32 v[26:27], v[18:19], v[18:19]
	v_mul_f32_e32 v18, 0x4b800000, v32
	v_cmp_gt_f32_e32 vcc, s5, v32
	v_pk_mul_f32 v[20:21], v[20:21], v[20:21]
	v_pk_mul_f32 v[24:25], v[16:17], v[16:17]
	v_max_f32_e32 v16, 0, v22
	v_max_f32_e32 v17, 0, v23
	v_cndmask_b32_e32 v18, v32, v18, vcc
	v_pk_mul_f32 v[22:23], v[16:17], v[16:17]
	v_cvt_pk_bf16_f32 v16, v20, v21
	v_rsq_f32_e32 v20, v18
	v_cvt_pk_bf16_f32 v17, v22, v23
	v_cvt_pk_bf16_f32 v18, v24, v25
	v_cvt_pk_bf16_f32 v19, v26, v27
	global_store_dwordx4 v[34:35], v[16:19], off offset:64
	s_mov_b32 s0, 0x160000
	s_mov_b64 s[4:5], 0x160000
	v_mul_f32_e32 v16, 0x45800000, v20
	v_cndmask_b32_e32 v16, v20, v16, vcc
	v_pk_mul_f32 v[12:13], v[12:13], v[16:17] op_sel_hi:[1,0]
	v_pk_mul_f32 v[8:9], v[8:9], v[16:17] op_sel_hi:[1,0]
	v_pk_mul_f32 v[14:15], v[14:15], v[16:17] op_sel_hi:[1,0]
	v_pk_mul_f32 v[10:11], v[10:11], v[16:17] op_sel_hi:[1,0]
	v_max_f32_e32 v12, 0, v12
	v_max_f32_e32 v8, 0, v8
	v_max_f32_e32 v13, 0, v13
	v_max_f32_e32 v9, 0, v9
	v_pk_mul_f32 v[12:13], v[12:13], v[12:13]
	v_pk_mul_f32 v[18:19], v[8:9], v[8:9]
	v_max_f32_e32 v8, 0, v14
	v_max_f32_e32 v10, 0, v10
	v_max_f32_e32 v9, 0, v15
	v_max_f32_e32 v11, 0, v11
	v_pk_mul_f32 v[14:15], v[8:9], v[8:9]
	v_pk_mul_f32 v[20:21], v[10:11], v[10:11]
	v_cvt_pk_bf16_f32 v8, v12, v13
	v_add_co_u32_e32 v12, vcc, s0, v130
	v_pk_mul_f32 v[0:1], v[0:1], v[16:17] op_sel_hi:[1,0]
	v_cvt_pk_bf16_f32 v9, v14, v15
	v_cvt_pk_bf16_f32 v10, v18, v19
	v_cvt_pk_bf16_f32 v11, v20, v21
	v_addc_co_u32_e32 v13, vcc, 0, v131, vcc
	v_pk_mul_f32 v[6:7], v[6:7], v[16:17] op_sel_hi:[1,0]
	v_pk_mul_f32 v[4:5], v[4:5], v[16:17] op_sel_hi:[1,0]
	v_pk_mul_f32 v[2:3], v[2:3], v[16:17] op_sel_hi:[1,0]
	v_max_f32_e32 v0, 0, v0
	v_max_f32_e32 v1, 0, v1
	global_store_dwordx4 v[12:13], v[8:11], off
	v_max_f32_e32 v4, 0, v4
	v_max_f32_e32 v5, 0, v5
	v_pk_mul_f32 v[8:9], v[0:1], v[0:1]
	v_max_f32_e32 v0, 0, v6
	v_max_f32_e32 v2, 0, v2
	v_max_f32_e32 v1, 0, v7
	v_max_f32_e32 v3, 0, v3
	v_pk_mul_f32 v[4:5], v[4:5], v[4:5]
	v_pk_mul_f32 v[6:7], v[0:1], v[0:1]
	v_pk_mul_f32 v[10:11], v[2:3], v[2:3]
	v_lshl_add_u64 v[22:23], v[130:131], 0, s[4:5]
	v_cvt_pk_bf16_f32 v0, v4, v5
	v_cvt_pk_bf16_f32 v1, v6, v7
	v_cvt_pk_bf16_f32 v2, v8, v9
	v_cvt_pk_bf16_f32 v3, v10, v11
	global_store_dwordx4 v[22:23], v[0:3], off offset:64
	s_waitcnt vmcnt(0)
	s_sub_i32 s0, s2, s49
	v_mov_b32_e32 v41, v175
	s_cmp_lt_u32 s0, 0x7ffffc00
	s_barrier
	s_cmp_lg_u32 s100, 0
	s_cbranch_scc1 .Lrd_old
	s_add_i32 s98, s2, 0x300
	s_mov_b32 s99, 0
	s_movk_i32 s101, 64
	s_branch .Lrd_entry
.Lrd_old:
	s_cmp_lt_u32 s0, 0x7ffffc00
	s_cbranch_scc1 .LBB0_786
	s_add_i32 s54, s0, 0x400
	s_ashr_i32 s7, s54, 7
	s_bfe_u32 s8, s0, 0x50002
	s_lshl_b32 s0, s7, 11
	s_lshl_b32 s4, s8, 6
	s_or_b32 s6, s4, s0
	v_ashrrev_i32_e32 v118, 4, v41
	v_add_u32_e32 v10, 0x200, v41
	s_and_b32 s10, s2, 3
	v_lshlrev_b32_e32 v34, 3, v41
	v_add_u32_e32 v0, s6, v118
	s_movk_i32 s9, 0x1600
	v_mov_b64_e32 v[8:9], s[74:75]
	v_ashrrev_i32_e32 v119, 4, v10
	v_and_b32_e32 v2, 0x78, v34
	v_mad_i64_i32 v[0:1], s[4:5], v0, s9, v[8:9]
	s_lshl_b32 s0, s10, 8
	v_add_u32_e32 v10, s6, v119
	v_lshl_add_u64 v[0:1], v[0:1], 0, s[0:1]
	v_lshlrev_b32_e32 v128, 1, v2
	v_mad_i64_i32 v[8:9], s[4:5], v10, s9, v[8:9]
	v_lshl_add_u64 v[24:25], v[0:1], 0, v[128:129]
	v_lshl_add_u64 v[8:9], v[8:9], 0, s[0:1]
	global_load_dwordx4 v[0:3], v[24:25], off offset:1536 nt
	global_load_dwordx4 v[4:7], v[24:25], off offset:2560 nt
	v_lshl_add_u64 v[26:27], v[8:9], 0, v[128:129]
	global_load_dwordx4 v[8:11], v[24:25], off offset:3584 nt
	global_load_dwordx4 v[12:15], v[26:27], off offset:1536 nt
	global_load_dwordx4 v[16:19], v[26:27], off offset:2560 nt
	global_load_dwordx4 v[20:23], v[26:27], off offset:3584 nt
	s_lshl_b32 s0, s7, 5
	s_max_u32 s1, s8, 1
	s_or_b32 s0, s0, s1
	s_add_i32 s0, s0, -1
	s_ashr_i32 s1, s0, 31
	s_lshl_b64 s[0:1], s[0:1], 17
	s_add_u32 s0, s46, s0
	s_addc_u32 s1, s3, s1
	s_lshl_b32 s11, s10, 15
	s_add_u32 s4, s0, s11
	s_addc_u32 s5, s1, 0
	s_cmp_lg_u32 s8, 0
	s_cselect_b64 s[0:1], -1, 0
	v_lshl_add_u64 v[32:33], s[4:5], 0, v[128:129]
	s_and_b64 vcc, exec, s[0:1]
	s_cbranch_vccz .LBB0_833
	v_and_b32_e32 v68, 0xffffff80, v34
	v_add_u32_e32 v24, 0x1000, v68
	v_ashrrev_i32_e32 v69, 31, v68
	v_ashrrev_i32_e32 v25, 31, v24
	v_lshl_add_u64 v[38:39], v[68:69], 1, v[32:33]
	v_lshl_add_u64 v[36:37], v[24:25], 1, v[32:33]
	global_load_dwordx4 v[28:31], v[38:39], off nt
	global_load_dwordx4 v[24:27], v[36:37], off nt
	s_cbranch_execnz .LBB0_765
